# in-proj layer-0 epilogue: the 8 gate-bias words loaded once per unit up front instead of a load+vmcnt(0)+store chain per word
# baseline (speedup 1.0000x reference)
.LBB0_591:
	v_lshl_add_u32 v142, s6, 8, v146
	v_lshl_or_b32 v140, s4, 8, v148
	v_ashrrev_i32_e32 v143, 31, v142
	v_lshlrev_b64 v[144:145], 6, v[142:143]
	v_cmp_lt_i32_e32 vcc, s0, v140
	s_and_saveexec_b64 s[4:5], vcc
	s_xor_b64 s[6:7], exec, s[4:5]
	s_cbranch_execz .LBB0_595
	s_movk_i32 s4, 0xb10
	v_cmp_gt_u32_e64 s[4:5], s4, v140
	s_and_saveexec_b64 s[24:25], s[4:5]
	s_cbranch_execz .LBB0_594
	v_add_u32_e32 v176, 0xfffff500, v140
	v_readlane_b32 s80, v254, 24
	v_lshl_add_u64 v[150:151], s[12:13], 0, v[144:145]
	v_lshlrev_b64 v[152:153], 2, v[176:177]
	v_readlane_b32 s81, v254, 25
	v_lshl_add_u64 v[150:151], v[150:151], 0, v[152:153]
	v_readlane_b32 s82, v254, 26
	v_lshl_add_u64 v[152:153], s[80:81], 0, v[152:153]
	global_load_dword v178, v[152:153], off
	global_load_dword v179, v[152:153], off offset:4
	global_load_dword v180, v[152:153], off offset:8
	global_load_dword v181, v[152:153], off offset:12
	global_load_dword v182, v[152:153], off offset:16
	global_load_dword v183, v[152:153], off offset:20
	global_load_dword v184, v[152:153], off offset:24
	global_load_dword v185, v[152:153], off offset:28
	v_readlane_b32 s83, v254, 27
	v_readlane_b32 s84, v254, 28
	v_readlane_b32 s85, v254, 29
	v_readlane_b32 s86, v254, 30
	v_readlane_b32 s87, v254, 31
	v_readlane_b32 s88, v254, 32
	v_readlane_b32 s89, v254, 33
	v_readlane_b32 s90, v254, 34
	v_readlane_b32 s91, v254, 35
	v_readlane_b32 s92, v254, 36
	v_readlane_b32 s93, v254, 37
	v_readlane_b32 s94, v254, 38
	v_readlane_b32 s95, v254, 39
	s_waitcnt vmcnt(0)
	v_add_f32_e32 v141, v124, v178
	flat_store_dword v[150:151], v141
	v_add_f32_e32 v141, v125, v179
	flat_store_dword v[150:151], v141 offset:4
	v_add_f32_e32 v141, v126, v180
	flat_store_dword v[150:151], v141 offset:8
	v_add_f32_e32 v141, v127, v181
	flat_store_dword v[150:151], v141 offset:12
	v_add_f32_e32 v141, v120, v182
	flat_store_dword v[150:151], v141 offset:16
	v_add_f32_e32 v141, v121, v183
	flat_store_dword v[150:151], v141 offset:20
	v_add_f32_e32 v141, v122, v184
	flat_store_dword v[150:151], v141 offset:24
	v_add_f32_e32 v141, v123, v185
	flat_store_dword v[150:151], v141 offset:28

.LBB0_597:
	s_or_b64 exec, exec, s[4:5]
	v_or_b32_e32 v120, 0x80, v140
	v_cmp_lt_i32_e64 s[4:5], s0, v120
	s_and_saveexec_b64 s[6:7], s[4:5]
	s_xor_b64 s[24:25], exec, s[6:7]
	s_mov_b32 s55, 0x800000
	s_cbranch_execz .LBB0_601
	s_movk_i32 s6, 0xa90
	v_cmp_gt_u32_e64 s[6:7], s6, v140
	s_and_saveexec_b64 s[26:27], s[6:7]
	s_cbranch_execz .LBB0_600
	v_add_u32_e32 v176, 0xfffff580, v140
	v_readlane_b32 s80, v254, 24
	v_lshl_add_u64 v[120:121], s[12:13], 0, v[144:145]
	v_lshlrev_b64 v[122:123], 2, v[176:177]
	v_readlane_b32 s81, v254, 25
	v_lshl_add_u64 v[120:121], v[120:121], 0, v[122:123]
	v_readlane_b32 s82, v254, 26
	v_lshl_add_u64 v[122:123], s[80:81], 0, v[122:123]
	global_load_dword v178, v[122:123], off
	global_load_dword v179, v[122:123], off offset:4
	global_load_dword v180, v[122:123], off offset:8
	global_load_dword v181, v[122:123], off offset:12
	global_load_dword v182, v[122:123], off offset:16
	global_load_dword v183, v[122:123], off offset:20
	global_load_dword v184, v[122:123], off offset:24
	global_load_dword v185, v[122:123], off offset:28
	v_readlane_b32 s83, v254, 27
	v_readlane_b32 s84, v254, 28
	v_readlane_b32 s85, v254, 29
	v_readlane_b32 s86, v254, 30
	v_readlane_b32 s87, v254, 31
	v_readlane_b32 s88, v254, 32
	v_readlane_b32 s89, v254, 33
	v_readlane_b32 s90, v254, 34
	v_readlane_b32 s91, v254, 35
	v_readlane_b32 s92, v254, 36
	v_readlane_b32 s93, v254, 37
	v_readlane_b32 s94, v254, 38
	v_readlane_b32 s95, v254, 39
	s_waitcnt vmcnt(0)
	v_add_f32_e32 v124, v116, v178
	flat_store_dword v[120:121], v124
	v_add_f32_e32 v124, v117, v179
	flat_store_dword v[120:121], v124 offset:4
	v_add_f32_e32 v124, v118, v180
	flat_store_dword v[120:121], v124 offset:8
	v_add_f32_e32 v124, v119, v181
	flat_store_dword v[120:121], v124 offset:12
	v_add_f32_e32 v124, v112, v182
	flat_store_dword v[120:121], v124 offset:16
	v_add_f32_e32 v124, v113, v183
	flat_store_dword v[120:121], v124 offset:20
	v_add_f32_e32 v124, v114, v184
	flat_store_dword v[120:121], v124 offset:24
	v_add_f32_e32 v122, v115, v185
	flat_store_dword v[120:121], v122 offset:28

.LBB0_603:
	s_or_b64 exec, exec, s[6:7]
	v_or_b32_e32 v112, 16, v142
	v_ashrrev_i32_e32 v113, 31, v112
	v_lshlrev_b64 v[114:115], 6, v[112:113]
	s_and_saveexec_b64 s[6:7], vcc
	s_xor_b64 s[24:25], exec, s[6:7]
	s_cbranch_execz .LBB0_611
	s_movk_i32 s6, 0xb10
	v_cmp_gt_u32_e64 s[6:7], s6, v140
	s_and_saveexec_b64 s[26:27], s[6:7]
	s_cbranch_execz .LBB0_606
	v_add_u32_e32 v176, 0xfffff500, v140
	v_readlane_b32 s80, v254, 24
	v_lshl_add_u64 v[116:117], s[12:13], 0, v[114:115]
	v_lshlrev_b64 v[118:119], 2, v[176:177]
	v_readlane_b32 s81, v254, 25
	v_lshl_add_u64 v[116:117], v[116:117], 0, v[118:119]
	v_readlane_b32 s82, v254, 26
	v_lshl_add_u64 v[118:119], s[80:81], 0, v[118:119]
	v_readlane_b32 s83, v254, 27
	v_readlane_b32 s84, v254, 28
	v_readlane_b32 s85, v254, 29
	v_readlane_b32 s86, v254, 30
	v_readlane_b32 s87, v254, 31
	v_readlane_b32 s88, v254, 32
	v_readlane_b32 s89, v254, 33
	v_readlane_b32 s90, v254, 34
	v_readlane_b32 s91, v254, 35
	v_readlane_b32 s92, v254, 36
	v_readlane_b32 s93, v254, 37
	v_readlane_b32 s94, v254, 38
	v_readlane_b32 s95, v254, 39
	v_add_f32_e32 v113, v108, v178
	flat_store_dword v[116:117], v113
	v_add_f32_e32 v113, v109, v179
	flat_store_dword v[116:117], v113 offset:4
	v_add_f32_e32 v113, v110, v180
	flat_store_dword v[116:117], v113 offset:8
	v_add_f32_e32 v113, v111, v181
	flat_store_dword v[116:117], v113 offset:12
	v_add_f32_e32 v113, v104, v182
	flat_store_dword v[116:117], v113 offset:16
	v_add_f32_e32 v113, v105, v183
	flat_store_dword v[116:117], v113 offset:20
	v_add_f32_e32 v113, v106, v184
	flat_store_dword v[116:117], v113 offset:24
	v_add_f32_e32 v113, v107, v185
	flat_store_dword v[116:117], v113 offset:28

.LBB0_608:
	s_movk_i32 s6, 0xa90
	v_cmp_gt_u32_e64 s[6:7], s6, v140
	s_and_saveexec_b64 s[26:27], s[6:7]
	s_cbranch_execz .LBB0_610
	v_add_u32_e32 v176, 0xfffff580, v140
	v_readlane_b32 s80, v254, 24
	v_lshl_add_u64 v[104:105], s[12:13], 0, v[114:115]
	v_lshlrev_b64 v[106:107], 2, v[176:177]
	v_readlane_b32 s81, v254, 25
	v_lshl_add_u64 v[104:105], v[104:105], 0, v[106:107]
	v_readlane_b32 s82, v254, 26
	v_lshl_add_u64 v[106:107], s[80:81], 0, v[106:107]
	global_load_dword v178, v[106:107], off
	global_load_dword v179, v[106:107], off offset:4
	global_load_dword v180, v[106:107], off offset:8
	global_load_dword v181, v[106:107], off offset:12
	global_load_dword v182, v[106:107], off offset:16
	global_load_dword v183, v[106:107], off offset:20
	global_load_dword v184, v[106:107], off offset:24
	global_load_dword v185, v[106:107], off offset:28
	v_readlane_b32 s83, v254, 27
	v_readlane_b32 s84, v254, 28
	v_readlane_b32 s85, v254, 29
	v_readlane_b32 s86, v254, 30
	v_readlane_b32 s87, v254, 31
	v_readlane_b32 s88, v254, 32
	v_readlane_b32 s89, v254, 33
	v_readlane_b32 s90, v254, 34
	v_readlane_b32 s91, v254, 35
	v_readlane_b32 s92, v254, 36
	v_readlane_b32 s93, v254, 37
	v_readlane_b32 s94, v254, 38
	v_readlane_b32 s95, v254, 39
	s_waitcnt vmcnt(0)
	v_add_f32_e32 v108, v100, v178
	flat_store_dword v[104:105], v108
	v_add_f32_e32 v108, v101, v179
	flat_store_dword v[104:105], v108 offset:4
	v_add_f32_e32 v108, v102, v180
	flat_store_dword v[104:105], v108 offset:8
	v_add_f32_e32 v108, v103, v181
	flat_store_dword v[104:105], v108 offset:12
	v_add_f32_e32 v108, v96, v182
	flat_store_dword v[104:105], v108 offset:16
	v_add_f32_e32 v108, v97, v183
	flat_store_dword v[104:105], v108 offset:20
	v_add_f32_e32 v108, v98, v184
	flat_store_dword v[104:105], v108 offset:24
	v_add_f32_e32 v106, v99, v185
	flat_store_dword v[104:105], v106 offset:28

.LBB0_615:
	s_or_b64 exec, exec, s[6:7]
	v_or_b32_e32 v96, 32, v142
	v_ashrrev_i32_e32 v97, 31, v96
	v_lshlrev_b64 v[98:99], 6, v[96:97]
	s_and_saveexec_b64 s[6:7], vcc
	s_xor_b64 s[24:25], exec, s[6:7]
	s_cbranch_execz .LBB0_623
	s_movk_i32 s6, 0xb10
	v_cmp_gt_u32_e64 s[6:7], s6, v140
	s_and_saveexec_b64 s[26:27], s[6:7]
	s_cbranch_execz .LBB0_618
	v_add_u32_e32 v176, 0xfffff500, v140
	v_readlane_b32 s80, v254, 24
	v_lshl_add_u64 v[100:101], s[12:13], 0, v[98:99]
	v_lshlrev_b64 v[102:103], 2, v[176:177]
	v_readlane_b32 s81, v254, 25
	v_lshl_add_u64 v[100:101], v[100:101], 0, v[102:103]
	v_readlane_b32 s82, v254, 26
	v_lshl_add_u64 v[102:103], s[80:81], 0, v[102:103]
	v_readlane_b32 s83, v254, 27
	v_readlane_b32 s84, v254, 28
	v_readlane_b32 s85, v254, 29
	v_readlane_b32 s86, v254, 30
	v_readlane_b32 s87, v254, 31
	v_readlane_b32 s88, v254, 32
	v_readlane_b32 s89, v254, 33
	v_readlane_b32 s90, v254, 34
	v_readlane_b32 s91, v254, 35
	v_readlane_b32 s92, v254, 36
	v_readlane_b32 s93, v254, 37
	v_readlane_b32 s94, v254, 38
	v_readlane_b32 s95, v254, 39
	v_add_f32_e32 v97, v92, v178
	flat_store_dword v[100:101], v97
	v_add_f32_e32 v97, v93, v179
	flat_store_dword v[100:101], v97 offset:4
	v_add_f32_e32 v97, v94, v180
	flat_store_dword v[100:101], v97 offset:8
	v_add_f32_e32 v97, v95, v181
	flat_store_dword v[100:101], v97 offset:12
	v_add_f32_e32 v97, v88, v182
	flat_store_dword v[100:101], v97 offset:16
	v_add_f32_e32 v97, v89, v183
	flat_store_dword v[100:101], v97 offset:20
	v_add_f32_e32 v97, v90, v184
	flat_store_dword v[100:101], v97 offset:24
	v_add_f32_e32 v97, v91, v185
	flat_store_dword v[100:101], v97 offset:28

.LBB0_620:
	s_movk_i32 s6, 0xa90
	v_cmp_gt_u32_e64 s[6:7], s6, v140
	s_and_saveexec_b64 s[26:27], s[6:7]
	s_cbranch_execz .LBB0_622
	v_add_u32_e32 v176, 0xfffff580, v140
	v_readlane_b32 s80, v254, 24
	v_lshl_add_u64 v[88:89], s[12:13], 0, v[98:99]
	v_lshlrev_b64 v[90:91], 2, v[176:177]
	v_readlane_b32 s81, v254, 25
	v_lshl_add_u64 v[88:89], v[88:89], 0, v[90:91]
	v_readlane_b32 s82, v254, 26
	v_lshl_add_u64 v[90:91], s[80:81], 0, v[90:91]
	global_load_dword v178, v[90:91], off
	global_load_dword v179, v[90:91], off offset:4
	global_load_dword v180, v[90:91], off offset:8
	global_load_dword v181, v[90:91], off offset:12
	global_load_dword v182, v[90:91], off offset:16
	global_load_dword v183, v[90:91], off offset:20
	global_load_dword v184, v[90:91], off offset:24
	global_load_dword v185, v[90:91], off offset:28
	v_readlane_b32 s83, v254, 27
	v_readlane_b32 s84, v254, 28
	v_readlane_b32 s85, v254, 29
	v_readlane_b32 s86, v254, 30
	v_readlane_b32 s87, v254, 31
	v_readlane_b32 s88, v254, 32
	v_readlane_b32 s89, v254, 33
	v_readlane_b32 s90, v254, 34
	v_readlane_b32 s91, v254, 35
	v_readlane_b32 s92, v254, 36
	v_readlane_b32 s93, v254, 37
	v_readlane_b32 s94, v254, 38
	v_readlane_b32 s95, v254, 39
	s_waitcnt vmcnt(0)
	v_add_f32_e32 v92, v84, v178
	flat_store_dword v[88:89], v92
	v_add_f32_e32 v92, v85, v179
	flat_store_dword v[88:89], v92 offset:4
	v_add_f32_e32 v92, v86, v180
	flat_store_dword v[88:89], v92 offset:8
	v_add_f32_e32 v92, v87, v181
	flat_store_dword v[88:89], v92 offset:12
	v_add_f32_e32 v92, v80, v182
	flat_store_dword v[88:89], v92 offset:16
	v_add_f32_e32 v92, v81, v183
	flat_store_dword v[88:89], v92 offset:20
	v_add_f32_e32 v92, v82, v184
	flat_store_dword v[88:89], v92 offset:24
	v_add_f32_e32 v90, v83, v185
	flat_store_dword v[88:89], v90 offset:28

.LBB0_627:
	s_or_b64 exec, exec, s[6:7]
	v_or_b32_e32 v80, 48, v142
	v_ashrrev_i32_e32 v81, 31, v80
	v_lshlrev_b64 v[82:83], 6, v[80:81]
	s_and_saveexec_b64 s[6:7], vcc
	s_xor_b64 s[24:25], exec, s[6:7]
	s_cbranch_execz .LBB0_635
	s_movk_i32 s6, 0xb10
	v_cmp_gt_u32_e64 s[6:7], s6, v140
	s_and_saveexec_b64 s[26:27], s[6:7]
	s_cbranch_execz .LBB0_630
	v_add_u32_e32 v176, 0xfffff500, v140
	v_readlane_b32 s80, v254, 24
	v_lshl_add_u64 v[84:85], s[12:13], 0, v[82:83]
	v_lshlrev_b64 v[86:87], 2, v[176:177]
	v_readlane_b32 s81, v254, 25
	v_lshl_add_u64 v[84:85], v[84:85], 0, v[86:87]
	v_readlane_b32 s82, v254, 26
	v_lshl_add_u64 v[86:87], s[80:81], 0, v[86:87]
	v_readlane_b32 s83, v254, 27
	v_readlane_b32 s84, v254, 28
	v_readlane_b32 s85, v254, 29
	v_readlane_b32 s86, v254, 30
	v_readlane_b32 s87, v254, 31
	v_readlane_b32 s88, v254, 32
	v_readlane_b32 s89, v254, 33
	v_readlane_b32 s90, v254, 34
	v_readlane_b32 s91, v254, 35
	v_readlane_b32 s92, v254, 36
	v_readlane_b32 s93, v254, 37
	v_readlane_b32 s94, v254, 38
	v_readlane_b32 s95, v254, 39
	v_add_f32_e32 v81, v76, v178
	flat_store_dword v[84:85], v81
	v_add_f32_e32 v81, v77, v179
	flat_store_dword v[84:85], v81 offset:4
	v_add_f32_e32 v81, v78, v180
	flat_store_dword v[84:85], v81 offset:8
	v_add_f32_e32 v81, v79, v181
	flat_store_dword v[84:85], v81 offset:12
	v_add_f32_e32 v81, v72, v182
	flat_store_dword v[84:85], v81 offset:16
	v_add_f32_e32 v81, v73, v183
	flat_store_dword v[84:85], v81 offset:20
	v_add_f32_e32 v81, v74, v184
	flat_store_dword v[84:85], v81 offset:24
	v_add_f32_e32 v81, v75, v185
	flat_store_dword v[84:85], v81 offset:28

.LBB0_632:
	s_movk_i32 s6, 0xa90
	v_cmp_gt_u32_e64 s[6:7], s6, v140
	s_and_saveexec_b64 s[26:27], s[6:7]
	s_cbranch_execz .LBB0_634
	v_add_u32_e32 v176, 0xfffff580, v140
	v_readlane_b32 s80, v254, 24
	v_lshl_add_u64 v[72:73], s[12:13], 0, v[82:83]
	v_lshlrev_b64 v[74:75], 2, v[176:177]
	v_readlane_b32 s81, v254, 25
	v_lshl_add_u64 v[72:73], v[72:73], 0, v[74:75]
	v_readlane_b32 s82, v254, 26
	v_lshl_add_u64 v[74:75], s[80:81], 0, v[74:75]
	global_load_dword v178, v[74:75], off
	global_load_dword v179, v[74:75], off offset:4
	global_load_dword v180, v[74:75], off offset:8
	global_load_dword v181, v[74:75], off offset:12
	global_load_dword v182, v[74:75], off offset:16
	global_load_dword v183, v[74:75], off offset:20
	global_load_dword v184, v[74:75], off offset:24
	global_load_dword v185, v[74:75], off offset:28
	v_readlane_b32 s83, v254, 27
	v_readlane_b32 s84, v254, 28
	v_readlane_b32 s85, v254, 29
	v_readlane_b32 s86, v254, 30
	v_readlane_b32 s87, v254, 31
	v_readlane_b32 s88, v254, 32
	v_readlane_b32 s89, v254, 33
	v_readlane_b32 s90, v254, 34
	v_readlane_b32 s91, v254, 35
	v_readlane_b32 s92, v254, 36
	v_readlane_b32 s93, v254, 37
	v_readlane_b32 s94, v254, 38
	v_readlane_b32 s95, v254, 39
	s_waitcnt vmcnt(0)
	v_add_f32_e32 v76, v68, v178
	flat_store_dword v[72:73], v76
	v_add_f32_e32 v76, v69, v179
	flat_store_dword v[72:73], v76 offset:4
	v_add_f32_e32 v76, v70, v180
	flat_store_dword v[72:73], v76 offset:8
	v_add_f32_e32 v76, v71, v181
	flat_store_dword v[72:73], v76 offset:12
	v_add_f32_e32 v76, v64, v182
	flat_store_dword v[72:73], v76 offset:16
	v_add_f32_e32 v76, v65, v183
	flat_store_dword v[72:73], v76 offset:20
	v_add_f32_e32 v76, v66, v184
	flat_store_dword v[72:73], v76 offset:24
	v_add_f32_e32 v74, v67, v185
	flat_store_dword v[72:73], v74 offset:28

.LBB0_639:
	s_or_b64 exec, exec, s[6:7]
	v_add_u32_e32 v64, 0x80, v142
	v_ashrrev_i32_e32 v65, 31, v64
	v_lshlrev_b64 v[66:67], 6, v[64:65]
	s_and_saveexec_b64 s[6:7], vcc
	s_xor_b64 s[24:25], exec, s[6:7]
	s_cbranch_execz .LBB0_647
	s_movk_i32 s6, 0xb10
	v_cmp_gt_u32_e64 s[6:7], s6, v140
	s_and_saveexec_b64 s[26:27], s[6:7]
	s_cbranch_execz .LBB0_642
	v_add_u32_e32 v176, 0xfffff500, v140
	v_readlane_b32 s80, v254, 24
	v_lshl_add_u64 v[68:69], s[12:13], 0, v[66:67]
	v_lshlrev_b64 v[70:71], 2, v[176:177]
	v_readlane_b32 s81, v254, 25
	v_lshl_add_u64 v[68:69], v[68:69], 0, v[70:71]
	v_readlane_b32 s82, v254, 26
	v_lshl_add_u64 v[70:71], s[80:81], 0, v[70:71]
	v_readlane_b32 s83, v254, 27
	v_readlane_b32 s84, v254, 28
	v_readlane_b32 s85, v254, 29
	v_readlane_b32 s86, v254, 30
	v_readlane_b32 s87, v254, 31
	v_readlane_b32 s88, v254, 32
	v_readlane_b32 s89, v254, 33
	v_readlane_b32 s90, v254, 34
	v_readlane_b32 s91, v254, 35
	v_readlane_b32 s92, v254, 36
	v_readlane_b32 s93, v254, 37
	v_readlane_b32 s94, v254, 38
	v_readlane_b32 s95, v254, 39
	v_add_f32_e32 v65, v60, v178
	flat_store_dword v[68:69], v65
	v_add_f32_e32 v65, v61, v179
	flat_store_dword v[68:69], v65 offset:4
	v_add_f32_e32 v65, v62, v180
	flat_store_dword v[68:69], v65 offset:8
	v_add_f32_e32 v65, v63, v181
	flat_store_dword v[68:69], v65 offset:12
	v_add_f32_e32 v65, v56, v182
	flat_store_dword v[68:69], v65 offset:16
	v_add_f32_e32 v65, v57, v183
	flat_store_dword v[68:69], v65 offset:20
	v_add_f32_e32 v65, v58, v184
	flat_store_dword v[68:69], v65 offset:24
	v_add_f32_e32 v65, v59, v185
	flat_store_dword v[68:69], v65 offset:28

.LBB0_644:
	s_movk_i32 s6, 0xa90
	v_cmp_gt_u32_e64 s[6:7], s6, v140
	s_and_saveexec_b64 s[26:27], s[6:7]
	s_cbranch_execz .LBB0_646
	v_add_u32_e32 v176, 0xfffff580, v140
	v_readlane_b32 s80, v254, 24
	v_lshl_add_u64 v[56:57], s[12:13], 0, v[66:67]
	v_lshlrev_b64 v[58:59], 2, v[176:177]
	v_readlane_b32 s81, v254, 25
	v_lshl_add_u64 v[56:57], v[56:57], 0, v[58:59]
	v_readlane_b32 s82, v254, 26
	v_lshl_add_u64 v[58:59], s[80:81], 0, v[58:59]
	global_load_dword v178, v[58:59], off
	global_load_dword v179, v[58:59], off offset:4
	global_load_dword v180, v[58:59], off offset:8
	global_load_dword v181, v[58:59], off offset:12
	global_load_dword v182, v[58:59], off offset:16
	global_load_dword v183, v[58:59], off offset:20
	global_load_dword v184, v[58:59], off offset:24
	global_load_dword v185, v[58:59], off offset:28
	v_readlane_b32 s83, v254, 27
	v_readlane_b32 s84, v254, 28
	v_readlane_b32 s85, v254, 29
	v_readlane_b32 s86, v254, 30
	v_readlane_b32 s87, v254, 31
	v_readlane_b32 s88, v254, 32
	v_readlane_b32 s89, v254, 33
	v_readlane_b32 s90, v254, 34
	v_readlane_b32 s91, v254, 35
	v_readlane_b32 s92, v254, 36
	v_readlane_b32 s93, v254, 37
	v_readlane_b32 s94, v254, 38
	v_readlane_b32 s95, v254, 39
	s_waitcnt vmcnt(0)
	v_add_f32_e32 v60, v52, v178
	flat_store_dword v[56:57], v60
	v_add_f32_e32 v60, v53, v179
	flat_store_dword v[56:57], v60 offset:4
	v_add_f32_e32 v60, v54, v180
	flat_store_dword v[56:57], v60 offset:8
	v_add_f32_e32 v60, v55, v181
	flat_store_dword v[56:57], v60 offset:12
	v_add_f32_e32 v60, v48, v182
	flat_store_dword v[56:57], v60 offset:16
	v_add_f32_e32 v60, v49, v183
	flat_store_dword v[56:57], v60 offset:20
	v_add_f32_e32 v60, v50, v184
	flat_store_dword v[56:57], v60 offset:24
	v_add_f32_e32 v58, v51, v185
	flat_store_dword v[56:57], v58 offset:28

.LBB0_651:
	s_or_b64 exec, exec, s[6:7]
	v_add_u32_e32 v48, 0x90, v142
	v_ashrrev_i32_e32 v49, 31, v48
	v_lshlrev_b64 v[50:51], 6, v[48:49]
	s_and_saveexec_b64 s[6:7], vcc
	s_xor_b64 s[24:25], exec, s[6:7]
	s_cbranch_execz .LBB0_659
	s_movk_i32 s6, 0xb10
	v_cmp_gt_u32_e64 s[6:7], s6, v140
	s_and_saveexec_b64 s[26:27], s[6:7]
	s_cbranch_execz .LBB0_654
	v_add_u32_e32 v176, 0xfffff500, v140
	v_readlane_b32 s80, v254, 24
	v_lshl_add_u64 v[52:53], s[12:13], 0, v[50:51]
	v_lshlrev_b64 v[54:55], 2, v[176:177]
	v_readlane_b32 s81, v254, 25
	v_lshl_add_u64 v[52:53], v[52:53], 0, v[54:55]
	v_readlane_b32 s82, v254, 26
	v_lshl_add_u64 v[54:55], s[80:81], 0, v[54:55]
	v_readlane_b32 s83, v254, 27
	v_readlane_b32 s84, v254, 28
	v_readlane_b32 s85, v254, 29
	v_readlane_b32 s86, v254, 30
	v_readlane_b32 s87, v254, 31
	v_readlane_b32 s88, v254, 32
	v_readlane_b32 s89, v254, 33
	v_readlane_b32 s90, v254, 34
	v_readlane_b32 s91, v254, 35
	v_readlane_b32 s92, v254, 36
	v_readlane_b32 s93, v254, 37
	v_readlane_b32 s94, v254, 38
	v_readlane_b32 s95, v254, 39
	v_add_f32_e32 v49, v44, v178
	flat_store_dword v[52:53], v49
	v_add_f32_e32 v49, v45, v179
	flat_store_dword v[52:53], v49 offset:4
	v_add_f32_e32 v49, v46, v180
	flat_store_dword v[52:53], v49 offset:8
	v_add_f32_e32 v49, v47, v181
	flat_store_dword v[52:53], v49 offset:12
	v_add_f32_e32 v49, v40, v182
	flat_store_dword v[52:53], v49 offset:16
	v_add_f32_e32 v49, v41, v183
	flat_store_dword v[52:53], v49 offset:20
	v_add_f32_e32 v49, v42, v184
	flat_store_dword v[52:53], v49 offset:24
	v_add_f32_e32 v49, v43, v185
	flat_store_dword v[52:53], v49 offset:28

.LBB0_656:
	s_movk_i32 s6, 0xa90
	v_cmp_gt_u32_e64 s[6:7], s6, v140
	s_and_saveexec_b64 s[26:27], s[6:7]
	s_cbranch_execz .LBB0_658
	v_add_u32_e32 v176, 0xfffff580, v140
	v_readlane_b32 s80, v254, 24
	v_lshl_add_u64 v[40:41], s[12:13], 0, v[50:51]
	v_lshlrev_b64 v[42:43], 2, v[176:177]
	v_readlane_b32 s81, v254, 25
	v_lshl_add_u64 v[40:41], v[40:41], 0, v[42:43]
	v_readlane_b32 s82, v254, 26
	v_lshl_add_u64 v[42:43], s[80:81], 0, v[42:43]
	global_load_dword v178, v[42:43], off
	global_load_dword v179, v[42:43], off offset:4
	global_load_dword v180, v[42:43], off offset:8
	global_load_dword v181, v[42:43], off offset:12
	global_load_dword v182, v[42:43], off offset:16
	global_load_dword v183, v[42:43], off offset:20
	global_load_dword v184, v[42:43], off offset:24
	global_load_dword v185, v[42:43], off offset:28
	v_readlane_b32 s83, v254, 27
	v_readlane_b32 s84, v254, 28
	v_readlane_b32 s85, v254, 29
	v_readlane_b32 s86, v254, 30
	v_readlane_b32 s87, v254, 31
	v_readlane_b32 s88, v254, 32
	v_readlane_b32 s89, v254, 33
	v_readlane_b32 s90, v254, 34
	v_readlane_b32 s91, v254, 35
	v_readlane_b32 s92, v254, 36
	v_readlane_b32 s93, v254, 37
	v_readlane_b32 s94, v254, 38
	v_readlane_b32 s95, v254, 39
	s_waitcnt vmcnt(0)
	v_add_f32_e32 v44, v36, v178
	flat_store_dword v[40:41], v44
	v_add_f32_e32 v44, v37, v179
	flat_store_dword v[40:41], v44 offset:4
	v_add_f32_e32 v44, v38, v180
	flat_store_dword v[40:41], v44 offset:8
	v_add_f32_e32 v44, v39, v181
	flat_store_dword v[40:41], v44 offset:12
	v_add_f32_e32 v44, v32, v182
	flat_store_dword v[40:41], v44 offset:16
	v_add_f32_e32 v44, v33, v183
	flat_store_dword v[40:41], v44 offset:20
	v_add_f32_e32 v44, v34, v184
	flat_store_dword v[40:41], v44 offset:24
	v_add_f32_e32 v42, v35, v185
	flat_store_dword v[40:41], v42 offset:28

.LBB0_663:
	s_or_b64 exec, exec, s[6:7]
	v_add_u32_e32 v32, 0xa0, v142
	v_ashrrev_i32_e32 v33, 31, v32
	v_lshlrev_b64 v[34:35], 6, v[32:33]
	s_and_saveexec_b64 s[6:7], vcc
	s_xor_b64 s[24:25], exec, s[6:7]
	s_cbranch_execz .LBB0_671
	s_movk_i32 s6, 0xb10
	v_cmp_gt_u32_e64 s[6:7], s6, v140
	s_and_saveexec_b64 s[26:27], s[6:7]
	s_cbranch_execz .LBB0_666
	v_add_u32_e32 v176, 0xfffff500, v140
	v_readlane_b32 s80, v254, 24
	v_lshl_add_u64 v[36:37], s[12:13], 0, v[34:35]
	v_lshlrev_b64 v[38:39], 2, v[176:177]
	v_readlane_b32 s81, v254, 25
	v_lshl_add_u64 v[36:37], v[36:37], 0, v[38:39]
	v_readlane_b32 s82, v254, 26
	v_lshl_add_u64 v[38:39], s[80:81], 0, v[38:39]
	v_readlane_b32 s83, v254, 27
	v_readlane_b32 s84, v254, 28
	v_readlane_b32 s85, v254, 29
	v_readlane_b32 s86, v254, 30
	v_readlane_b32 s87, v254, 31
	v_readlane_b32 s88, v254, 32
	v_readlane_b32 s89, v254, 33
	v_readlane_b32 s90, v254, 34
	v_readlane_b32 s91, v254, 35
	v_readlane_b32 s92, v254, 36
	v_readlane_b32 s93, v254, 37
	v_readlane_b32 s94, v254, 38
	v_readlane_b32 s95, v254, 39
	v_add_f32_e32 v33, v28, v178
	flat_store_dword v[36:37], v33
	v_add_f32_e32 v33, v29, v179
	flat_store_dword v[36:37], v33 offset:4
	v_add_f32_e32 v33, v30, v180
	flat_store_dword v[36:37], v33 offset:8
	v_add_f32_e32 v33, v31, v181
	flat_store_dword v[36:37], v33 offset:12
	v_add_f32_e32 v33, v24, v182
	flat_store_dword v[36:37], v33 offset:16
	v_add_f32_e32 v33, v25, v183
	flat_store_dword v[36:37], v33 offset:20
	v_add_f32_e32 v33, v26, v184
	flat_store_dword v[36:37], v33 offset:24
	v_add_f32_e32 v33, v27, v185
	flat_store_dword v[36:37], v33 offset:28

.LBB0_668:
	s_movk_i32 s6, 0xa90
	v_cmp_gt_u32_e64 s[6:7], s6, v140
	s_and_saveexec_b64 s[26:27], s[6:7]
	s_cbranch_execz .LBB0_670
	v_add_u32_e32 v176, 0xfffff580, v140
	v_readlane_b32 s80, v254, 24
	v_lshl_add_u64 v[24:25], s[12:13], 0, v[34:35]
	v_lshlrev_b64 v[26:27], 2, v[176:177]
	v_readlane_b32 s81, v254, 25
	v_lshl_add_u64 v[24:25], v[24:25], 0, v[26:27]
	v_readlane_b32 s82, v254, 26
	v_lshl_add_u64 v[26:27], s[80:81], 0, v[26:27]
	global_load_dword v178, v[26:27], off
	global_load_dword v179, v[26:27], off offset:4
	global_load_dword v180, v[26:27], off offset:8
	global_load_dword v181, v[26:27], off offset:12
	global_load_dword v182, v[26:27], off offset:16
	global_load_dword v183, v[26:27], off offset:20
	global_load_dword v184, v[26:27], off offset:24
	global_load_dword v185, v[26:27], off offset:28
	v_readlane_b32 s83, v254, 27
	v_readlane_b32 s84, v254, 28
	v_readlane_b32 s85, v254, 29
	v_readlane_b32 s86, v254, 30
	v_readlane_b32 s87, v254, 31
	v_readlane_b32 s88, v254, 32
	v_readlane_b32 s89, v254, 33
	v_readlane_b32 s90, v254, 34
	v_readlane_b32 s91, v254, 35
	v_readlane_b32 s92, v254, 36
	v_readlane_b32 s93, v254, 37
	v_readlane_b32 s94, v254, 38
	v_readlane_b32 s95, v254, 39
	s_waitcnt vmcnt(0)
	v_add_f32_e32 v28, v20, v178
	flat_store_dword v[24:25], v28
	v_add_f32_e32 v28, v21, v179
	flat_store_dword v[24:25], v28 offset:4
	v_add_f32_e32 v28, v22, v180
	flat_store_dword v[24:25], v28 offset:8
	v_add_f32_e32 v28, v23, v181
	flat_store_dword v[24:25], v28 offset:12
	v_add_f32_e32 v28, v16, v182
	flat_store_dword v[24:25], v28 offset:16
	v_add_f32_e32 v28, v17, v183
	flat_store_dword v[24:25], v28 offset:20
	v_add_f32_e32 v28, v18, v184
	flat_store_dword v[24:25], v28 offset:24
	v_add_f32_e32 v26, v19, v185
	flat_store_dword v[24:25], v26 offset:28

.LBB0_675:
	s_or_b64 exec, exec, s[6:7]
	v_add_u32_e32 v16, 0xb0, v142
	v_ashrrev_i32_e32 v17, 31, v16
	v_lshlrev_b64 v[18:19], 6, v[16:17]
	s_and_saveexec_b64 s[6:7], vcc
	s_xor_b64 s[6:7], exec, s[6:7]
	s_cbranch_execz .LBB0_684
	s_movk_i32 s17, 0xb10
	v_cmp_gt_u32_e32 vcc, s17, v140
	s_and_saveexec_b64 s[24:25], vcc
	s_cbranch_execz .LBB0_678
	v_add_u32_e32 v176, 0xfffff500, v140
	v_readlane_b32 s80, v254, 24
	v_lshl_add_u64 v[20:21], s[12:13], 0, v[18:19]
	v_lshlrev_b64 v[22:23], 2, v[176:177]
	v_readlane_b32 s81, v254, 25
	v_lshl_add_u64 v[20:21], v[20:21], 0, v[22:23]
	v_readlane_b32 s82, v254, 26
	v_lshl_add_u64 v[22:23], s[80:81], 0, v[22:23]
	v_readlane_b32 s83, v254, 27
	v_readlane_b32 s84, v254, 28
	v_readlane_b32 s85, v254, 29
	v_readlane_b32 s86, v254, 30
	v_readlane_b32 s87, v254, 31
	v_readlane_b32 s88, v254, 32
	v_readlane_b32 s89, v254, 33
	v_readlane_b32 s90, v254, 34
	v_readlane_b32 s91, v254, 35
	v_readlane_b32 s92, v254, 36
	v_readlane_b32 s93, v254, 37
	v_readlane_b32 s94, v254, 38
	v_readlane_b32 s95, v254, 39
	v_add_f32_e32 v17, v12, v178
	flat_store_dword v[20:21], v17
	v_add_f32_e32 v17, v13, v179
	flat_store_dword v[20:21], v17 offset:4
	v_add_f32_e32 v17, v14, v180
	flat_store_dword v[20:21], v17 offset:8
	v_add_f32_e32 v17, v15, v181
	flat_store_dword v[20:21], v17 offset:12
	v_add_f32_e32 v17, v8, v182
	flat_store_dword v[20:21], v17 offset:16
	v_add_f32_e32 v17, v9, v183
	flat_store_dword v[20:21], v17 offset:20
	v_add_f32_e32 v17, v10, v184
	flat_store_dword v[20:21], v17 offset:24
	v_add_f32_e32 v17, v11, v185
	flat_store_dword v[20:21], v17 offset:28

.LBB0_680:
	s_movk_i32 s6, 0xa90
	v_cmp_gt_u32_e32 vcc, s6, v140
	s_and_saveexec_b64 s[6:7], vcc
	s_cbranch_execz .LBB0_682
	v_add_u32_e32 v176, 0xfffff580, v140
	v_readlane_b32 s80, v254, 24
	v_lshl_add_u64 v[8:9], s[12:13], 0, v[18:19]
	v_lshlrev_b64 v[10:11], 2, v[176:177]
	v_readlane_b32 s81, v254, 25
	v_lshl_add_u64 v[8:9], v[8:9], 0, v[10:11]
	v_readlane_b32 s82, v254, 26
	v_lshl_add_u64 v[10:11], s[80:81], 0, v[10:11]
	global_load_dword v178, v[10:11], off
	global_load_dword v179, v[10:11], off offset:4
	global_load_dword v180, v[10:11], off offset:8
	global_load_dword v181, v[10:11], off offset:12
	global_load_dword v182, v[10:11], off offset:16
	global_load_dword v183, v[10:11], off offset:20
	global_load_dword v184, v[10:11], off offset:24
	global_load_dword v185, v[10:11], off offset:28
	v_readlane_b32 s83, v254, 27
	v_readlane_b32 s84, v254, 28
	v_readlane_b32 s85, v254, 29
	v_readlane_b32 s86, v254, 30
	v_readlane_b32 s87, v254, 31
	v_readlane_b32 s88, v254, 32
	v_readlane_b32 s89, v254, 33
	v_readlane_b32 s90, v254, 34
	v_readlane_b32 s91, v254, 35
	v_readlane_b32 s92, v254, 36
	v_readlane_b32 s93, v254, 37
	v_readlane_b32 s94, v254, 38
	v_readlane_b32 s95, v254, 39
	s_waitcnt vmcnt(0)
	v_add_f32_e32 v12, v4, v178
	flat_store_dword v[8:9], v12
	v_add_f32_e32 v12, v5, v179
	flat_store_dword v[8:9], v12 offset:4
	v_add_f32_e32 v12, v6, v180
	flat_store_dword v[8:9], v12 offset:8
	v_add_f32_e32 v12, v7, v181
	flat_store_dword v[8:9], v12 offset:12
	v_add_f32_e32 v12, v0, v182
	flat_store_dword v[8:9], v12 offset:16
	v_add_f32_e32 v12, v1, v183
	flat_store_dword v[8:9], v12 offset:20
	v_add_f32_e32 v12, v2, v184
	flat_store_dword v[8:9], v12 offset:24
	v_add_f32_e32 v10, v3, v185
	flat_store_dword v[8:9], v10 offset:28
